# top-k radix select starts at bit 29: bit 30 is never set for softmax probabilities <= 1.0 (exact), one fewer sync round per item
# speedup vs baseline: 1.0073x; 1.0073x over previous
.LtkA_item:
	s_lshr_b32 s2, s33, 4
	s_and_b32 s3, s33, 15
	v_lshl_add_u32 v1, s2, 12, v250
	s_lshl_b32 s6, s3, 2
	v_lshlrev_b32_e32 v2, 6, v1
	v_add_u32_e32 v2, s6, v2
	s_mov_b64 s[6:7], s[76:77]
	global_load_dword v16, v2, s[6:7]
	s_add_u32 s6, s6, 0x4000
	s_addc_u32 s7, s7, 0
	global_load_dword v17, v2, s[6:7]
	s_add_u32 s6, s6, 0x4000
	s_addc_u32 s7, s7, 0
	global_load_dword v18, v2, s[6:7]
	s_add_u32 s6, s6, 0x4000
	s_addc_u32 s7, s7, 0
	global_load_dword v19, v2, s[6:7]
	s_add_u32 s6, s6, 0x4000
	s_addc_u32 s7, s7, 0
	global_load_dword v20, v2, s[6:7]
	s_add_u32 s6, s6, 0x4000
	s_addc_u32 s7, s7, 0
	global_load_dword v21, v2, s[6:7]
	s_add_u32 s6, s6, 0x4000
	s_addc_u32 s7, s7, 0
	global_load_dword v22, v2, s[6:7]
	s_add_u32 s6, s6, 0x4000
	s_addc_u32 s7, s7, 0
	global_load_dword v23, v2, s[6:7]
	s_add_u32 s6, s6, 0x4000
	s_addc_u32 s7, s7, 0
	global_load_dword v24, v2, s[6:7]
	s_add_u32 s6, s6, 0x4000
	s_addc_u32 s7, s7, 0
	global_load_dword v25, v2, s[6:7]
	s_add_u32 s6, s6, 0x4000
	s_addc_u32 s7, s7, 0
	global_load_dword v26, v2, s[6:7]
	s_add_u32 s6, s6, 0x4000
	s_addc_u32 s7, s7, 0
	global_load_dword v27, v2, s[6:7]
	s_add_u32 s6, s6, 0x4000
	s_addc_u32 s7, s7, 0
	global_load_dword v28, v2, s[6:7]
	s_add_u32 s6, s6, 0x4000
	s_addc_u32 s7, s7, 0
	global_load_dword v29, v2, s[6:7]
	s_add_u32 s6, s6, 0x4000
	s_addc_u32 s7, s7, 0
	global_load_dword v30, v2, s[6:7]
	s_add_u32 s6, s6, 0x4000
	s_addc_u32 s7, s7, 0
	global_load_dword v31, v2, s[6:7]
	v_cmp_eq_u32_e32 vcc, 0, v250
	s_and_saveexec_b64 s[0:1], vcc
	v_mov_b32_e32 v4, 0
	v_mov_b32_e32 v5, 48
	ds_write_b32 v5, v4
	s_mov_b64 exec, s[0:1]
	s_lshl_b32 s27, s3, 10
	s_lshl_b32 s18, s2, 9
	s_add_u32 s27, s27, s18
	s_lshl_b32 s18, s27, 2
	s_add_u32 s36, s78, s18
	s_addc_u32 s37, s79, 0
	s_add_u32 s38, s80, s18
	s_addc_u32 s39, s81, 0
	s_mov_b32 s4, 29
	s_mov_b32 s5, 0
	s_mov_b32 s8, 0
	s_waitcnt vmcnt(0)
